# grid barrier: non-leader workgroups issue buffer_wbl2 on arrival so the XCD leader's release write-back finds the L2 mostly clean
# speedup vs baseline: 1.0015x; 1.0005x over previous
; __device__ __forceinline__ unsigned xb_ld(unsigned* p)              { return __hip_atomic_load(p, __ATOMIC_RELAXED, __HIP_MEMORY_SCOPE_AGENT); }
; __device__ __forceinline__ unsigned xb_add(unsigned* p, unsigned v) { return __hip_atomic_fetch_add(p, v, __ATOMIC_RELAXED, __HIP_MEMORY_SCOPE_AGENT); }
; #define XB_SPIN(cond, bar) do { unsigned _sp = 0; while (cond) { __builtin_amdgcn_s_sleep(1); \
;     if ((++_sp & 255u) == 0u) { if (xb_ld(&(bar)[XB_TMO])) break; if (_sp > XB_SPIN_CAP) { atomicAdd(&(bar)[XB_TMO], 1u); break; } } } } while (0)
; __device__ __forceinline__ void xcd_barrier(const XcdBarrier& b) {
;     ...
;         const unsigned old = xb_add(&bar[XB_XSUB(b.x)], 1u);
;         const unsigned gen = old / nloc;
;         if (old + 1u == (gen + 1u) * nloc) {
;             __builtin_amdgcn_fence(__ATOMIC_RELEASE, "agent");
;             asm volatile("s_waitcnt vmcnt(0)" ::: "memory");
;             const unsigned og = xb_add(&bar[XB_TOP], 1u);
;             const unsigned tg = og / nx;
;             if (og + 1u == (tg + 1u) * nx) xb_add(&bar[XB_TOPGEN], 1u);
;             else XB_SPIN(xb_ld(&bar[XB_TOPGEN]) == tg, bar);
;             __builtin_amdgcn_fence(__ATOMIC_ACQUIRE, "agent");
;             xb_add(&bar[XB_XGEN(b.x)], 1u);
;             asm volatile("s_waitcnt vmcnt(0)" ::: "memory");
;         } else {
;             XB_SPIN(xb_ld(&bar[XB_XGEN(b.x)]) == gen, bar);
;             __builtin_amdgcn_fence(__ATOMIC_ACQUIRE, "agent");
;             asm volatile("s_waitcnt vmcnt(0)" ::: "memory");
;         }
.LBB9_186:
	s_or_b64 exec, exec, s[14:15]
	s_waitcnt vmcnt(0)
	v_readfirstlane_b32 s4, v4
	v_cvt_f32_u32_e32 v4, v2
	v_sub_u32_e32 v5, 0, v2
	v_add_u32_e32 v3, s4, v3
	v_readlane_b32 s4, v254, 51
	v_rcp_iflag_f32_e32 v4, v4
	v_readlane_b32 s5, v254, 52
	s_mov_b64 s[14:15], -1
	v_mul_f32_e32 v4, 0x4f7ffffe, v4
	v_cvt_u32_f32_e32 v4, v4
	v_mul_lo_u32 v5, v5, v4
	v_mul_hi_u32 v5, v4, v5
	v_add_u32_e32 v4, v4, v5
	v_mul_hi_u32 v4, v3, v4
	v_mul_lo_u32 v5, v4, v2
	v_sub_u32_e32 v5, v3, v5
	v_cmp_ge_u32_e32 vcc, v5, v2
	v_add_u32_e32 v6, 1, v4
	v_add_u32_e32 v3, 1, v3
	v_cndmask_b32_e32 v4, v4, v6, vcc
	v_sub_u32_e32 v6, v5, v2
	v_cndmask_b32_e32 v5, v5, v6, vcc
	v_cmp_ge_u32_e32 vcc, v5, v2
	v_add_u32_e32 v5, 1, v4
	s_nop 0
	v_cndmask_b32_e32 v4, v4, v5, vcc
	v_mul_lo_u32 v5, v2, v4
	v_add_u32_e32 v2, v5, v2
	v_cmp_ne_u32_e32 vcc, v3, v2
	v_mov_b64_e32 v[2:3], s[4:5]
	s_and_saveexec_b64 s[10:11], vcc
	s_cbranch_execz .LBB9_198
	buffer_wbl2 sc1
	v_readlane_b32 s4, v254, 51
	v_readlane_b32 s5, v254, 52
	s_mov_b64 s[18:19], 0
	s_nop 3
	global_load_dword v2, v187, s[4:5] sc1
	s_waitcnt vmcnt(0)
	v_cmp_eq_u32_e32 vcc, v2, v4
	s_and_saveexec_b64 s[14:15], vcc
	s_cbranch_execz .LBB9_197
	s_mov_b32 s4, 1
	s_branch .LBB9_190

; __device__ __forceinline__ unsigned xb_ld(unsigned* p)              { return __hip_atomic_load(p, __ATOMIC_RELAXED, __HIP_MEMORY_SCOPE_AGENT); }
; __device__ __forceinline__ unsigned xb_add(unsigned* p, unsigned v) { return __hip_atomic_fetch_add(p, v, __ATOMIC_RELAXED, __HIP_MEMORY_SCOPE_AGENT); }
; #define XB_SPIN(cond, bar) do { unsigned _sp = 0; while (cond) { __builtin_amdgcn_s_sleep(1); \
;     if ((++_sp & 255u) == 0u) { if (xb_ld(&(bar)[XB_TMO])) break; if (_sp > XB_SPIN_CAP) { atomicAdd(&(bar)[XB_TMO], 1u); break; } } } } while (0)
; __device__ __forceinline__ void xcd_barrier(const XcdBarrier& b) {
;     ...
;         const unsigned old = xb_add(&bar[XB_XSUB(b.x)], 1u);
;         const unsigned gen = old / nloc;
;         if (old + 1u == (gen + 1u) * nloc) {
;             __builtin_amdgcn_fence(__ATOMIC_RELEASE, "agent");
;             asm volatile("s_waitcnt vmcnt(0)" ::: "memory");
;             const unsigned og = xb_add(&bar[XB_TOP], 1u);
;             const unsigned tg = og / nx;
;             if (og + 1u == (tg + 1u) * nx) xb_add(&bar[XB_TOPGEN], 1u);
;             else XB_SPIN(xb_ld(&bar[XB_TOPGEN]) == tg, bar);
;             __builtin_amdgcn_fence(__ATOMIC_ACQUIRE, "agent");
;             xb_add(&bar[XB_XGEN(b.x)], 1u);
;             asm volatile("s_waitcnt vmcnt(0)" ::: "memory");
;         } else {
;             XB_SPIN(xb_ld(&bar[XB_XGEN(b.x)]) == gen, bar);
;             __builtin_amdgcn_fence(__ATOMIC_ACQUIRE, "agent");
;             asm volatile("s_waitcnt vmcnt(0)" ::: "memory");
;         }
.LBB9_1027:
	s_or_b64 exec, exec, s[14:15]
	s_waitcnt vmcnt(0)
	v_readfirstlane_b32 s3, v4
	v_cvt_f32_u32_e32 v4, v2
	v_sub_u32_e32 v5, 0, v2
	v_add_u32_e32 v3, s3, v3
	v_readlane_b32 s4, v254, 51
	v_rcp_iflag_f32_e32 v4, v4
	v_readlane_b32 s5, v254, 52
	s_mov_b64 s[14:15], -1
	v_mul_f32_e32 v4, 0x4f7ffffe, v4
	v_cvt_u32_f32_e32 v4, v4
	v_mul_lo_u32 v5, v5, v4
	v_mul_hi_u32 v5, v4, v5
	v_add_u32_e32 v4, v4, v5
	v_mul_hi_u32 v4, v3, v4
	v_mul_lo_u32 v5, v4, v2
	v_sub_u32_e32 v5, v3, v5
	v_cmp_ge_u32_e32 vcc, v5, v2
	v_add_u32_e32 v6, 1, v4
	v_add_u32_e32 v3, 1, v3
	v_cndmask_b32_e32 v4, v4, v6, vcc
	v_sub_u32_e32 v6, v5, v2
	v_cndmask_b32_e32 v5, v5, v6, vcc
	v_cmp_ge_u32_e32 vcc, v5, v2
	v_add_u32_e32 v5, 1, v4
	s_nop 0
	v_cndmask_b32_e32 v4, v4, v5, vcc
	v_mul_lo_u32 v5, v2, v4
	v_add_u32_e32 v2, v5, v2
	v_cmp_ne_u32_e32 vcc, v3, v2
	v_mov_b64_e32 v[2:3], s[4:5]
	s_and_saveexec_b64 s[10:11], vcc
	s_cbranch_execz .LBB9_1039
	buffer_wbl2 sc1
	v_readlane_b32 s4, v254, 51
	v_readlane_b32 s5, v254, 52
	s_mov_b64 s[18:19], 0
	s_nop 3
	global_load_dword v2, v187, s[4:5] sc1
	s_waitcnt vmcnt(0)
	v_cmp_eq_u32_e32 vcc, v2, v4
	s_and_saveexec_b64 s[14:15], vcc
	s_cbranch_execz .LBB9_1038
	s_mov_b32 s4, 1
	s_branch .LBB9_1031

; __device__ __forceinline__ unsigned xb_ld(unsigned* p)              { return __hip_atomic_load(p, __ATOMIC_RELAXED, __HIP_MEMORY_SCOPE_AGENT); }
; __device__ __forceinline__ unsigned xb_add(unsigned* p, unsigned v) { return __hip_atomic_fetch_add(p, v, __ATOMIC_RELAXED, __HIP_MEMORY_SCOPE_AGENT); }
; #define XB_SPIN(cond, bar) do { unsigned _sp = 0; while (cond) { __builtin_amdgcn_s_sleep(1); \
;     if ((++_sp & 255u) == 0u) { if (xb_ld(&(bar)[XB_TMO])) break; if (_sp > XB_SPIN_CAP) { atomicAdd(&(bar)[XB_TMO], 1u); break; } } } } while (0)
; __device__ __forceinline__ void xcd_barrier(const XcdBarrier& b) {
;     ...
;         const unsigned old = xb_add(&bar[XB_XSUB(b.x)], 1u);
;         const unsigned gen = old / nloc;
;         if (old + 1u == (gen + 1u) * nloc) {
;             __builtin_amdgcn_fence(__ATOMIC_RELEASE, "agent");
;             asm volatile("s_waitcnt vmcnt(0)" ::: "memory");
;             const unsigned og = xb_add(&bar[XB_TOP], 1u);
;             const unsigned tg = og / nx;
;             if (og + 1u == (tg + 1u) * nx) xb_add(&bar[XB_TOPGEN], 1u);
;             else XB_SPIN(xb_ld(&bar[XB_TOPGEN]) == tg, bar);
;             __builtin_amdgcn_fence(__ATOMIC_ACQUIRE, "agent");
;             xb_add(&bar[XB_XGEN(b.x)], 1u);
;             asm volatile("s_waitcnt vmcnt(0)" ::: "memory");
;         } else {
;             XB_SPIN(xb_ld(&bar[XB_XGEN(b.x)]) == gen, bar);
;             __builtin_amdgcn_fence(__ATOMIC_ACQUIRE, "agent");
;             asm volatile("s_waitcnt vmcnt(0)" ::: "memory");
;         }
.LBB9_1706:
	s_or_b64 exec, exec, s[18:19]
	s_waitcnt vmcnt(0)
	v_readfirstlane_b32 s3, v4
	v_cvt_f32_u32_e32 v4, v2
	v_sub_u32_e32 v5, 0, v2
	v_add_u32_e32 v3, s3, v3
	v_readlane_b32 s4, v254, 51
	v_rcp_iflag_f32_e32 v4, v4
	v_readlane_b32 s5, v254, 52
	s_mov_b64 s[18:19], -1
	v_mul_f32_e32 v4, 0x4f7ffffe, v4
	v_cvt_u32_f32_e32 v4, v4
	v_mul_lo_u32 v5, v5, v4
	v_mul_hi_u32 v5, v4, v5
	v_add_u32_e32 v4, v4, v5
	v_mul_hi_u32 v4, v3, v4
	v_mul_lo_u32 v5, v4, v2
	v_sub_u32_e32 v5, v3, v5
	v_cmp_ge_u32_e32 vcc, v5, v2
	v_add_u32_e32 v6, 1, v4
	v_add_u32_e32 v3, 1, v3
	v_cndmask_b32_e32 v4, v4, v6, vcc
	v_sub_u32_e32 v6, v5, v2
	v_cndmask_b32_e32 v5, v5, v6, vcc
	v_cmp_ge_u32_e32 vcc, v5, v2
	v_add_u32_e32 v5, 1, v4
	s_nop 0
	v_cndmask_b32_e32 v4, v4, v5, vcc
	v_mul_lo_u32 v5, v2, v4
	v_add_u32_e32 v2, v5, v2
	v_cmp_ne_u32_e32 vcc, v3, v2
	v_mov_b64_e32 v[2:3], s[4:5]
	s_and_saveexec_b64 s[14:15], vcc
	s_cbranch_execz .LBB9_1718
	buffer_wbl2 sc1
	v_readlane_b32 s4, v254, 51
	v_readlane_b32 s5, v254, 52
	s_mov_b64 s[20:21], 0
	s_nop 3
	global_load_dword v2, v187, s[4:5] sc1
	s_waitcnt vmcnt(0)
	v_cmp_eq_u32_e32 vcc, v2, v4
	s_and_saveexec_b64 s[18:19], vcc
	s_cbranch_execz .LBB9_1717
	s_mov_b32 s4, 1
	s_branch .LBB9_1710
